# v52 with the preparation on 128 workgroups
# speedup vs baseline: 1.0517x; 1.0021x over previous
; #define LAS __attribute__((address_space(3)))
; __device__ __forceinline__ unsigned xb_ld(unsigned* p)              { return __hip_atomic_load(p, __ATOMIC_RELAXED, __HIP_MEMORY_SCOPE_AGENT); }
; __device__ __forceinline__ void sb_decode_wave_loop(const Params& P, float* lds) {
;     unsigned* qd = (unsigned*)(P.ws + WS_BAR) + QW_DEC;
;     const int lane = threadIdx.x & 63;
;     volatile LAS unsigned* scw = (volatile LAS unsigned*)((LAS unsigned char*)lds + SC_CTL_OFF_FWD);
;     unsigned nxt = 0u;
;     if (lane == 0) nxt = atomicAdd(qd, 2u);
;     for (;;) {
;         const int t = __builtin_amdgcn_readfirstlane((int)nxt);
;         if (t >= DEC_NTASK) break;
;         if (lane == 0) nxt = atomicAdd(qd, 2u);
; __device__ __forceinline__ void p3_scan_and_sb(const Params& P, float* lds) {
;     ...
;     if (blockIdx.x < 96) {
;         const int bh = blockIdx.x >> 2, quarter = blockIdx.x & 3, b = bh / RH, h = bh % RH;
;         volatile LAS unsigned* scw = (volatile LAS unsigned*)((LAS unsigned char*)lds + SC_CTL_OFF);
;         if (tid < 5) scw[tid] = 0u;
;         if (tid == 0) { XB_SPIN(xb_ld(ctl + QW_PREP_W) < (unsigned)NPREP, ctl); __builtin_amdgcn_fence(__ATOMIC_ACQUIRE, "agent"); asm volatile("s_waitcnt vmcnt(0)" ::: "memory"); }
;         __syncthreads();
;         scan_prompt_wave(P, (unsigned char*)lds, b, h, quarter);
;         if (wave >= 5 + SC_FREE_WAVES) {
;             constexpr unsigned NCHU = SEQ / SCH;
;             while (scw[1] < NCHU || scw[2] < NCHU || scw[3] < NCHU || scw[4] < NCHU) __builtin_amdgcn_s_sleep(32);
;         }
;     } else {
;         const int grp = wave >> 2, gw = wave & 3;
;         volatile LAS unsigned* gctl = (volatile LAS unsigned*)((LAS unsigned char*)lds + LDS_CTL + 32);
;         if (tid < 8) gctl[tid] = 0u;
;         __syncthreads();
;         sba::Grp4 G; G.ctr = gctl + grp; G.gen = 0u;
;         if (grp == 1) sb_decode_wave_loop(P, lds);
;         {
;             volatile LAS unsigned* qw = gctl + 4 + grp;
;             unsigned* qhead = (unsigned*)(P.ws + WS_BAR) + QW_SB;
;             const bool popper = (gw == 0 && lane == 0);
;             unsigned nxt = 0u;
;             if (popper) nxt = atomicAdd(qhead, 1u);
.LBB0_939:
	s_cmp_lt_i32 s60, 4
	s_cselect_b64 s[0:1], -1, 0
	s_cmp_gt_i32 s61, 3
	s_cselect_b64 s[2:3], -1, 0
	s_and_b64 s[34:35], s[0:1], s[2:3]
	s_andn2_b64 vcc, exec, s[34:35]
	s_cbranch_vccnz .LBB0_1576
	v_writelane_b32 v252, s34, 54
	s_cmpk_lt_u32 s56, 0x60
	v_and_b32_e32 v1, 63, v0
	v_writelane_b32 v252, s35, 55
	v_writelane_b32 v252, s80, 56
	s_cselect_b64 s[52:53], -1, 0
	s_cmpk_gt_u32 s56, 0x5f
	v_writelane_b32 v252, s81, 57
	v_writelane_b32 v252, s56, 53
	v_writelane_b32 v252, s60, 51
	s_mov_b64 s[0:1], -1
	s_waitcnt vmcnt(0)
	v_writelane_b32 v252, s61, 52
	s_barrier
	v_writelane_b32 v252, s57, 50
	s_cbranch_scc0 .LBB0_1203
	v_writelane_b32 v252, s52, 58
	v_cmp_gt_u32_e32 vcc, 8, v0
	s_nop 0
	v_writelane_b32 v252, s53, 59
	s_and_saveexec_b64 s[0:1], vcc
	v_lshl_add_u32 v2, v0, 2, 0
	v_add_u32_e32 v2, 0x26020, v2
	v_mov_b32_e32 v3, 0
	ds_write_b32 v2, v3
	s_or_b64 exec, exec, s[0:1]
	v_lshrrev_b32_e32 v94, 8, v0
	s_waitcnt lgkmcnt(0)
	s_barrier
	v_cmp_eq_u32_e32 vcc, 1, v94
	s_mov_b64 s[0:1], exec
	v_writelane_b32 v252, s0, 60
	s_nop 1
	v_writelane_b32 v252, s1, 61
	s_cmpk_gt_u32 s56, 0x7f
	s_cselect_b64 s[2:3], exec, 0
	s_or_b64 vcc, vcc, s[2:3]
	s_and_b64 s[0:1], s[0:1], vcc
	s_mov_b64 exec, s[0:1]
	s_cbranch_execz .LBB0_1092
	v_readfirstlane_b32 s2, v94
	s_cmp_eq_u32 s2, 0
	s_cselect_b32 s100, 2, 0x7fffffff
	s_add_u32 s0, s78, 0x3900
	s_addc_u32 s1, s79, 0
	v_writelane_b32 v252, s0, 62
	v_mov_b32_e32 v95, 0
	v_cmp_eq_u32_e64 s[4:5], 0, v1
	v_writelane_b32 v252, s1, 63
	s_and_saveexec_b64 s[0:1], s[4:5]
	v_readlane_b32 s22, v252, 48
	v_readlane_b32 s23, v252, 49
	s_cbranch_execz .LBB0_948
	s_mov_b64 s[6:7], exec
	v_mbcnt_lo_u32_b32 v2, s6, 0
	v_mbcnt_hi_u32_b32 v2, s7, v2
	v_cmp_eq_u32_e32 vcc, 0, v2
	s_and_saveexec_b64 s[2:3], vcc
	s_cbranch_execz .LBB0_947
	s_bcnt1_i32_b64 s6, s[6:7]
	s_lshl_b32 s6, s6, 1
	v_mov_b32_e32 v4, s6
	v_readlane_b32 s6, v252, 62
	v_mov_b32_e32 v3, 0
	v_readlane_b32 s7, v252, 63
	s_nop 4
	global_atomic_add v3, v3, v4, s[6:7] sc0
